# GEMM main loop: loop-invariant A-fragment LDS read addresses precomputed per tile (4 VALU per iteration removed from the loading wave)
# speedup vs baseline: 1.0215x; 1.0015x over previous
; #define PG8_STAGE(bufoff, gbase, voff) do { _Pragma("unroll") for (int _i = 0; _i < 2; ++_i) \
;         __builtin_amdgcn_global_load_lds((const unsigned*)((const char*)(gbase) + (voff)[_i]), (LAS unsigned*)(lds + (bufoff) + ldsw + _i * 8192), 16, 0, 0); } while (0)
; #define PG8_LDA(dst, b, h) do { _Pragma("unroll") for (int m = 0; m < 4; ++m) _Pragma("unroll") for (int k = 0; k < 2; ++k) dst[m][k] = *(const LAS bf16x8*)(lds + PG8_SA(b, h) + aoff + m * 2048 + k * 1024); } while (0)
; #define PG8_LDB(dst, b, h) do { _Pragma("unroll") for (int n = 0; n < 2; ++n) _Pragma("unroll") for (int k = 0; k < 2; ++k) dst[n][k] = *(const LAS bf16x8*)(lds + PG8_SB(b, h) + boff + n * 2048 + k * 1024); } while (0)
; #define PG8_MMA(ai, bj, At, Bt) do { __builtin_amdgcn_s_setprio(1); _Pragma("unroll") for (int m = 0; m < 4; ++m) _Pragma("unroll") for (int n = 0; n < 2; ++n) _Pragma("unroll") for (int k = 0; k < 2; ++k) \
;         acc[ai][bj][m][n] = __builtin_amdgcn_mfma_f32_16x16x32_bf16(Bt[n][k], At[m][k], acc[ai][bj][m][n], 0, 0, 0); __builtin_amdgcn_s_setprio(0); } while (0)
; #define PG8_WAIT_V(n) asm volatile("s_waitcnt vmcnt(" #n ")" ::: "memory")
; #define PG8_WAIT_L(n) asm volatile("s_waitcnt lgkmcnt(" #n ")" ::: "memory")
; #define PG8_BAR __builtin_amdgcn_s_barrier()
; #define PG8_SCHED __builtin_amdgcn_sched_barrier(0)
; __device__ __forceinline__ void gemm_phase(LAS unsigned char* lds, const GemmD g, const Sched& S, const Epi& E) {
;     ...
;         for (int t = 0; t < nt; t += 2) {
;             const bool last = (t == nt - 2);
;             const char* a1 = cA + (size_t)(t + 1) * kstep;
;             const char* a2 = last ? nA : cA + (size_t)(t + 2) * kstep; const char* b2 = last ? nB : cB + (size_t)(t + 2) * kstep;
;             const char* a3 = a2 + kstep; const char* b3 = b2 + kstep;
;             PG8_LDB(B0, 0, 0); PG8_LDB(B1, 0, 1); PG8_SCHED; PG8_LDA(At, 0, 0); PG8_STAGE(PG8_SA(1, 1), a1 + hstepA, voffA);
;             PG8_WAIT_V(8); PG8_WAIT_L(0); PG8_BAR; PG8_MMA(0, 0, At, B0); PG8_MMA(0, 1, At, B1); PG8_BAR; PG8_SCHED;
;             PG8_LDA(At, 0, 1); PG8_STAGE(PG8_SB(0, 0), b2, voffB); PG8_STAGE(PG8_SB(0, 1), b2 + hstepB, voffB); PG8_STAGE(PG8_SA(0, 0), a2, voffA);
;             PG8_WAIT_V(8); PG8_WAIT_L(0); PG8_BAR; PG8_MMA(1, 0, At, B0); PG8_MMA(1, 1, At, B1); PG8_BAR; PG8_SCHED;
.Lprio_done:
	v_add_u32_e32 v240, 0x10000, v160
	v_add_u32_e32 v241, 0x14000, v160
	v_add_u32_e32 v242, 0x18000, v160
	v_add_u32_e32 v243, 0x1c000, v160
.LBB0_215:
	s_add_i32 s92, s26, 2
	s_add_u32 s93, s8, 0x80
	s_addc_u32 s27, s9, 0
	s_add_i32 s22, 0, 0x10000
	s_cmp_eq_u32 s11, s26
	s_cselect_b32 s27, s1, s27
	s_cselect_b32 s26, s0, s93
	s_cselect_b32 vcc_hi, s17, s35
	s_cselect_b32 vcc_lo, s16, s34
	s_add_i32 s23, 0, 0x14000
	ds_read_b128 v[130:133], v240
	ds_read_b128 v[146:149], v240 offset:1024
	ds_read_b128 v[150:153], v240 offset:2048
	ds_read_b128 v[154:157], v240 offset:3072
	ds_read_b128 v[162:165], v241
	ds_read_b128 v[166:169], v241 offset:1024
	ds_read_b128 v[170:173], v241 offset:2048
	ds_read_b128 v[174:177], v241 offset:3072
	s_add_i32 m0, s31, 0xc000
	ds_read_b128 v[182:185], v161
	ds_read_b128 v[186:189], v161 offset:1024
	ds_read_b128 v[190:193], v161 offset:2048
	ds_read_b128 v[216:219], v161 offset:3072
	ds_read_b128 v[220:223], v161 offset:4096
	ds_read_b128 v[224:227], v161 offset:5120
	ds_read_b128 v[228:231], v161 offset:6144
	ds_read_b128 v[236:239], v161 offset:7168
	global_load_lds_dwordx4 v142, s[8:9]
	s_add_i32 m0, s31, 0xe000
	s_nop 0
	global_load_lds_dwordx4 v144, s[8:9]
	s_waitcnt vmcnt(8)
	s_waitcnt lgkmcnt(0)
	s_barrier
	s_waitcnt lgkmcnt(0)
	v_mfma_f32_16x16x32_bf16 v[126:129], v[130:133], v[182:185], v[126:129]
	v_mfma_f32_16x16x32_bf16 v[122:125], v[150:153], v[182:185], v[122:125]
	v_mfma_f32_16x16x32_bf16 v[110:113], v[130:133], v[190:193], v[110:113]
	v_mfma_f32_16x16x32_bf16 v[106:109], v[150:153], v[190:193], v[106:109]
	v_mfma_f32_16x16x32_bf16 v[94:97], v[130:133], v[220:223], v[94:97]
	v_mfma_f32_16x16x32_bf16 v[90:93], v[150:153], v[220:223], v[90:93]
	v_mfma_f32_16x16x32_bf16 v[78:81], v[130:133], v[228:231], v[78:81]
	v_mfma_f32_16x16x32_bf16 v[74:77], v[150:153], v[228:231], v[74:77]
	v_mfma_f32_16x16x32_bf16 v[126:129], v[146:149], v[186:189], v[126:129]
	v_mfma_f32_16x16x32_bf16 v[122:125], v[154:157], v[186:189], v[122:125]
	v_mfma_f32_16x16x32_bf16 v[110:113], v[146:149], v[216:219], v[110:113]
	v_mfma_f32_16x16x32_bf16 v[106:109], v[154:157], v[216:219], v[106:109]
	v_mfma_f32_16x16x32_bf16 v[94:97], v[146:149], v[224:227], v[94:97]
	v_mfma_f32_16x16x32_bf16 v[90:93], v[154:157], v[224:227], v[90:93]
	v_mfma_f32_16x16x32_bf16 v[78:81], v[146:149], v[236:239], v[78:81]
	v_mfma_f32_16x16x32_bf16 v[74:77], v[154:157], v[236:239], v[74:77]
	v_mfma_f32_16x16x32_bf16 v[118:121], v[162:165], v[182:185], v[118:121]
	v_mfma_f32_16x16x32_bf16 v[114:117], v[170:173], v[182:185], v[114:117]
	v_mfma_f32_16x16x32_bf16 v[102:105], v[162:165], v[190:193], v[102:105]
	v_mfma_f32_16x16x32_bf16 v[98:101], v[170:173], v[190:193], v[98:101]
	v_mfma_f32_16x16x32_bf16 v[86:89], v[162:165], v[220:223], v[86:89]
	v_mfma_f32_16x16x32_bf16 v[82:85], v[170:173], v[220:223], v[82:85]
	v_mfma_f32_16x16x32_bf16 v[70:73], v[162:165], v[228:231], v[70:73]
	v_mfma_f32_16x16x32_bf16 v[66:69], v[170:173], v[228:231], v[66:69]
	v_mfma_f32_16x16x32_bf16 v[118:121], v[166:169], v[186:189], v[118:121]
	v_mfma_f32_16x16x32_bf16 v[114:117], v[174:177], v[186:189], v[114:117]
	v_mfma_f32_16x16x32_bf16 v[102:105], v[166:169], v[216:219], v[102:105]
	v_mfma_f32_16x16x32_bf16 v[98:101], v[174:177], v[216:219], v[98:101]
	v_mfma_f32_16x16x32_bf16 v[86:89], v[166:169], v[224:227], v[86:89]
	v_mfma_f32_16x16x32_bf16 v[82:85], v[174:177], v[224:227], v[82:85]
	v_mfma_f32_16x16x32_bf16 v[70:73], v[166:169], v[236:239], v[70:73]
	v_mfma_f32_16x16x32_bf16 v[66:69], v[174:177], v[236:239], v[66:69]
	s_barrier
	s_add_i32 s22, s22, s30
	s_mov_b32 m0, s22
	ds_read_b128 v[182:185], v161 offset:16384
	ds_read_b128 v[186:189], v161 offset:17408
	ds_read_b128 v[190:193], v161 offset:18432
	ds_read_b128 v[216:219], v161 offset:19456
	ds_read_b128 v[220:223], v161 offset:20480
	ds_read_b128 v[224:227], v161 offset:21504
	ds_read_b128 v[228:231], v161 offset:22528
	ds_read_b128 v[236:239], v161 offset:23552
	global_load_lds_dwordx4 v136, vcc
	s_add_i32 m0, s22, 0x2000
	s_add_i32 s22, s23, s30
	global_load_lds_dwordx4 v140, vcc
	s_mov_b32 m0, s22
	s_nop 0
	global_load_lds_dwordx4 v253, vcc
	s_add_i32 m0, s22, 0x2000
	s_nop 0
	global_load_lds_dwordx4 v254, vcc
	s_mov_b32 m0, s31
	s_nop 0
	global_load_lds_dwordx4 v134, s[26:27]
	s_mov_b32 m0, s14
	s_nop 0
	global_load_lds_dwordx4 v138, s[26:27]
	s_waitcnt vmcnt(8)
	s_waitcnt lgkmcnt(0)
	s_barrier
	s_waitcnt lgkmcnt(0)
	v_mfma_f32_16x16x32_bf16 v[62:65], v[130:133], v[182:185], v[62:65]
	v_mfma_f32_16x16x32_bf16 v[58:61], v[150:153], v[182:185], v[58:61]
	v_mfma_f32_16x16x32_bf16 v[46:49], v[130:133], v[190:193], v[46:49]
	v_mfma_f32_16x16x32_bf16 v[42:45], v[150:153], v[190:193], v[42:45]
	v_mfma_f32_16x16x32_bf16 v[30:33], v[130:133], v[220:223], v[30:33]
	v_mfma_f32_16x16x32_bf16 v[26:29], v[150:153], v[220:223], v[26:29]
	v_mfma_f32_16x16x32_bf16 v[14:17], v[130:133], v[228:231], v[14:17]
	v_mfma_f32_16x16x32_bf16 v[10:13], v[150:153], v[228:231], v[10:13]
	v_mfma_f32_16x16x32_bf16 v[62:65], v[146:149], v[186:189], v[62:65]
	v_mfma_f32_16x16x32_bf16 v[58:61], v[154:157], v[186:189], v[58:61]
	v_mfma_f32_16x16x32_bf16 v[46:49], v[146:149], v[216:219], v[46:49]
	v_mfma_f32_16x16x32_bf16 v[42:45], v[154:157], v[216:219], v[42:45]
	v_mfma_f32_16x16x32_bf16 v[30:33], v[146:149], v[224:227], v[30:33]
	v_mfma_f32_16x16x32_bf16 v[26:29], v[154:157], v[224:227], v[26:29]
	v_mfma_f32_16x16x32_bf16 v[14:17], v[146:149], v[236:239], v[14:17]
	v_mfma_f32_16x16x32_bf16 v[10:13], v[154:157], v[236:239], v[10:13]
	v_mfma_f32_16x16x32_bf16 v[54:57], v[162:165], v[182:185], v[54:57]
	v_mfma_f32_16x16x32_bf16 v[50:53], v[170:173], v[182:185], v[50:53]
	v_mfma_f32_16x16x32_bf16 v[38:41], v[162:165], v[190:193], v[38:41]
	v_mfma_f32_16x16x32_bf16 v[34:37], v[170:173], v[190:193], v[34:37]
	v_mfma_f32_16x16x32_bf16 v[22:25], v[162:165], v[220:223], v[22:25]
	v_mfma_f32_16x16x32_bf16 v[18:21], v[170:173], v[220:223], v[18:21]
	v_mfma_f32_16x16x32_bf16 v[6:9], v[162:165], v[228:231], v[6:9]
	v_mfma_f32_16x16x32_bf16 v[2:5], v[170:173], v[228:231], v[2:5]
	v_mfma_f32_16x16x32_bf16 v[54:57], v[166:169], v[186:189], v[54:57]
	v_mfma_f32_16x16x32_bf16 v[50:53], v[174:177], v[186:189], v[50:53]
	v_mfma_f32_16x16x32_bf16 v[38:41], v[166:169], v[216:219], v[38:41]
	v_mfma_f32_16x16x32_bf16 v[34:37], v[174:177], v[216:219], v[34:37]
	v_mfma_f32_16x16x32_bf16 v[22:25], v[166:169], v[224:227], v[22:25]
	v_mfma_f32_16x16x32_bf16 v[18:21], v[174:177], v[224:227], v[18:21]
	v_mfma_f32_16x16x32_bf16 v[6:9], v[166:169], v[236:239], v[6:9]
	v_mfma_f32_16x16x32_bf16 v[2:5], v[174:177], v[236:239], v[2:5]
	s_barrier
; #define PG8_STAGE(bufoff, gbase, voff) do { _Pragma("unroll") for (int _i = 0; _i < 2; ++_i) \
;         __builtin_amdgcn_global_load_lds((const unsigned*)((const char*)(gbase) + (voff)[_i]), (LAS unsigned*)(lds + (bufoff) + ldsw + _i * 8192), 16, 0, 0); } while (0)
; #define PG8_LDA(dst, b, h) do { _Pragma("unroll") for (int m = 0; m < 4; ++m) _Pragma("unroll") for (int k = 0; k < 2; ++k) dst[m][k] = *(const LAS bf16x8*)(lds + PG8_SA(b, h) + aoff + m * 2048 + k * 1024); } while (0)
; #define PG8_LDB(dst, b, h) do { _Pragma("unroll") for (int n = 0; n < 2; ++n) _Pragma("unroll") for (int k = 0; k < 2; ++k) dst[n][k] = *(const LAS bf16x8*)(lds + PG8_SB(b, h) + boff + n * 2048 + k * 1024); } while (0)
; #define PG8_MMA(ai, bj, At, Bt) do { __builtin_amdgcn_s_setprio(1); _Pragma("unroll") for (int m = 0; m < 4; ++m) _Pragma("unroll") for (int n = 0; n < 2; ++n) _Pragma("unroll") for (int k = 0; k < 2; ++k) \
;         acc[ai][bj][m][n] = __builtin_amdgcn_mfma_f32_16x16x32_bf16(Bt[n][k], At[m][k], acc[ai][bj][m][n], 0, 0, 0); __builtin_amdgcn_s_setprio(0); } while (0)
; #define PG8_WAIT_V(n) asm volatile("s_waitcnt vmcnt(" #n ")" ::: "memory")
; #define PG8_WAIT_L(n) asm volatile("s_waitcnt lgkmcnt(" #n ")" ::: "memory")
; #define PG8_BAR __builtin_amdgcn_s_barrier()
; #define PG8_SCHED __builtin_amdgcn_sched_barrier(0)
; __device__ __forceinline__ void gemm_phase(LAS unsigned char* lds, const GemmD g, const Sched& S, const Epi& E) {
;     ...
;             PG8_LDB(B0, 1, 0); PG8_LDB(B1, 1, 1); PG8_SCHED; PG8_LDA(At, 1, 0); PG8_STAGE(PG8_SA(0, 1), a2 + hstepA, voffA);
;             PG8_WAIT_V(8); PG8_WAIT_L(0); PG8_BAR; PG8_MMA(0, 0, At, B0); PG8_MMA(0, 1, At, B1); PG8_BAR; PG8_SCHED;
;             PG8_LDA(At, 1, 1); PG8_STAGE(PG8_SB(1, 0), b3, voffB); PG8_STAGE(PG8_SB(1, 1), b3 + hstepB, voffB); PG8_STAGE(PG8_SA(1, 0), a3, voffA);
;             PG8_WAIT_V(8); PG8_WAIT_L(0); PG8_BAR; PG8_MMA(1, 0, At, B0); PG8_MMA(1, 1, At, B1); PG8_BAR; PG8_SCHED;
;         }
;         if (wr == 0) PG8_BAR;
;         epi_run(E, acc, cur, wr, wc, fr, fq);
	s_add_i32 s22, 0, 0x18000
	s_add_i32 s23, 0, 0x1c000
	ds_read_b128 v[130:133], v242
	ds_read_b128 v[146:149], v242 offset:1024
	ds_read_b128 v[150:153], v242 offset:2048
	ds_read_b128 v[154:157], v242 offset:3072
	ds_read_b128 v[162:165], v243
	ds_read_b128 v[166:169], v243 offset:1024
	ds_read_b128 v[170:173], v243 offset:2048
	ds_read_b128 v[174:177], v243 offset:3072
	s_mov_b32 m0, s15
	ds_read_b128 v[182:185], v161 offset:32768
	ds_read_b128 v[186:189], v161 offset:33792
	ds_read_b128 v[190:193], v161 offset:34816
	ds_read_b128 v[216:219], v161 offset:35840
	ds_read_b128 v[220:223], v161 offset:36864
	ds_read_b128 v[224:227], v161 offset:37888
	ds_read_b128 v[228:231], v161 offset:38912
	ds_read_b128 v[236:239], v161 offset:39936
	global_load_lds_dwordx4 v142, s[26:27]
	s_mov_b32 m0, s10
	s_nop 0
	global_load_lds_dwordx4 v144, s[26:27]
	s_waitcnt vmcnt(8)
	s_waitcnt lgkmcnt(0)
	s_barrier
	s_waitcnt lgkmcnt(0)
	v_mfma_f32_16x16x32_bf16 v[126:129], v[130:133], v[182:185], v[126:129]
	v_mfma_f32_16x16x32_bf16 v[122:125], v[150:153], v[182:185], v[122:125]
	v_mfma_f32_16x16x32_bf16 v[110:113], v[130:133], v[190:193], v[110:113]
	v_mfma_f32_16x16x32_bf16 v[106:109], v[150:153], v[190:193], v[106:109]
	v_mfma_f32_16x16x32_bf16 v[94:97], v[130:133], v[220:223], v[94:97]
	v_mfma_f32_16x16x32_bf16 v[90:93], v[150:153], v[220:223], v[90:93]
	v_mfma_f32_16x16x32_bf16 v[78:81], v[130:133], v[228:231], v[78:81]
	v_mfma_f32_16x16x32_bf16 v[74:77], v[150:153], v[228:231], v[74:77]
	v_mfma_f32_16x16x32_bf16 v[126:129], v[146:149], v[186:189], v[126:129]
	v_mfma_f32_16x16x32_bf16 v[122:125], v[154:157], v[186:189], v[122:125]
	v_mfma_f32_16x16x32_bf16 v[110:113], v[146:149], v[216:219], v[110:113]
	v_mfma_f32_16x16x32_bf16 v[106:109], v[154:157], v[216:219], v[106:109]
	v_mfma_f32_16x16x32_bf16 v[94:97], v[146:149], v[224:227], v[94:97]
	v_mfma_f32_16x16x32_bf16 v[90:93], v[154:157], v[224:227], v[90:93]
	v_mfma_f32_16x16x32_bf16 v[78:81], v[146:149], v[236:239], v[78:81]
	v_mfma_f32_16x16x32_bf16 v[74:77], v[154:157], v[236:239], v[74:77]
	v_mfma_f32_16x16x32_bf16 v[118:121], v[162:165], v[182:185], v[118:121]
	v_mfma_f32_16x16x32_bf16 v[114:117], v[170:173], v[182:185], v[114:117]
	v_mfma_f32_16x16x32_bf16 v[102:105], v[162:165], v[190:193], v[102:105]
	v_mfma_f32_16x16x32_bf16 v[98:101], v[170:173], v[190:193], v[98:101]
	v_mfma_f32_16x16x32_bf16 v[86:89], v[162:165], v[220:223], v[86:89]
	v_mfma_f32_16x16x32_bf16 v[82:85], v[170:173], v[220:223], v[82:85]
	v_mfma_f32_16x16x32_bf16 v[70:73], v[162:165], v[228:231], v[70:73]
	v_mfma_f32_16x16x32_bf16 v[66:69], v[170:173], v[228:231], v[66:69]
	v_mfma_f32_16x16x32_bf16 v[118:121], v[166:169], v[186:189], v[118:121]
	v_mfma_f32_16x16x32_bf16 v[114:117], v[174:177], v[186:189], v[114:117]
	v_mfma_f32_16x16x32_bf16 v[102:105], v[166:169], v[216:219], v[102:105]
	v_mfma_f32_16x16x32_bf16 v[98:101], v[174:177], v[216:219], v[98:101]
	v_mfma_f32_16x16x32_bf16 v[86:89], v[166:169], v[224:227], v[86:89]
	v_mfma_f32_16x16x32_bf16 v[82:85], v[174:177], v[224:227], v[82:85]
	v_mfma_f32_16x16x32_bf16 v[70:73], v[166:169], v[236:239], v[70:73]
	v_mfma_f32_16x16x32_bf16 v[66:69], v[174:177], v[236:239], v[66:69]
	s_barrier
	s_add_i32 s22, s22, s30
	s_add_u32 vcc_lo, vcc_lo, s84
	s_addc_u32 vcc_hi, vcc_hi, s85
	s_add_u32 s26, s26, s84
	s_addc_u32 s27, s27, s85
	s_mov_b32 m0, s22
	ds_read_b128 v[182:185], v161 offset:49152
	ds_read_b128 v[186:189], v161 offset:50176
	ds_read_b128 v[190:193], v161 offset:51200
	ds_read_b128 v[216:219], v161 offset:52224
	ds_read_b128 v[220:223], v161 offset:53248
	ds_read_b128 v[224:227], v161 offset:54272
	ds_read_b128 v[228:231], v161 offset:55296
	ds_read_b128 v[236:239], v161 offset:56320
	global_load_lds_dwordx4 v136, vcc
	s_add_i32 m0, s22, 0x2000
	s_add_i32 s22, s23, s30
	global_load_lds_dwordx4 v140, vcc
	s_mov_b32 m0, s22
	s_nop 0
	global_load_lds_dwordx4 v253, vcc
	s_add_i32 m0, s22, 0x2000
	s_nop 0
	global_load_lds_dwordx4 v254, vcc
	s_mov_b32 m0, s18
	s_nop 0
	global_load_lds_dwordx4 v134, s[26:27]
	s_mov_b32 m0, s19
	s_nop 0
	global_load_lds_dwordx4 v138, s[26:27]
	s_waitcnt vmcnt(8)
	s_waitcnt lgkmcnt(0)
	s_barrier
	s_waitcnt lgkmcnt(0)
	v_mfma_f32_16x16x32_bf16 v[62:65], v[130:133], v[182:185], v[62:65]
	v_mfma_f32_16x16x32_bf16 v[58:61], v[150:153], v[182:185], v[58:61]
	v_mfma_f32_16x16x32_bf16 v[46:49], v[130:133], v[190:193], v[46:49]
	v_mfma_f32_16x16x32_bf16 v[42:45], v[150:153], v[190:193], v[42:45]
	v_mfma_f32_16x16x32_bf16 v[30:33], v[130:133], v[220:223], v[30:33]
	v_mfma_f32_16x16x32_bf16 v[26:29], v[150:153], v[220:223], v[26:29]
	v_mfma_f32_16x16x32_bf16 v[14:17], v[130:133], v[228:231], v[14:17]
	v_mfma_f32_16x16x32_bf16 v[10:13], v[150:153], v[228:231], v[10:13]
	v_mfma_f32_16x16x32_bf16 v[62:65], v[146:149], v[186:189], v[62:65]
	v_mfma_f32_16x16x32_bf16 v[58:61], v[154:157], v[186:189], v[58:61]
	v_mfma_f32_16x16x32_bf16 v[46:49], v[146:149], v[216:219], v[46:49]
	v_mfma_f32_16x16x32_bf16 v[42:45], v[154:157], v[216:219], v[42:45]
	v_mfma_f32_16x16x32_bf16 v[30:33], v[146:149], v[224:227], v[30:33]
	v_mfma_f32_16x16x32_bf16 v[26:29], v[154:157], v[224:227], v[26:29]
	v_mfma_f32_16x16x32_bf16 v[14:17], v[146:149], v[236:239], v[14:17]
	v_mfma_f32_16x16x32_bf16 v[10:13], v[154:157], v[236:239], v[10:13]
	v_mfma_f32_16x16x32_bf16 v[54:57], v[162:165], v[182:185], v[54:57]
	v_mfma_f32_16x16x32_bf16 v[50:53], v[170:173], v[182:185], v[50:53]
	v_mfma_f32_16x16x32_bf16 v[38:41], v[162:165], v[190:193], v[38:41]
	v_mfma_f32_16x16x32_bf16 v[34:37], v[170:173], v[190:193], v[34:37]
	v_mfma_f32_16x16x32_bf16 v[22:25], v[162:165], v[220:223], v[22:25]
	v_mfma_f32_16x16x32_bf16 v[18:21], v[170:173], v[220:223], v[18:21]
	v_mfma_f32_16x16x32_bf16 v[6:9], v[162:165], v[228:231], v[6:9]
	v_mfma_f32_16x16x32_bf16 v[2:5], v[170:173], v[228:231], v[2:5]
	v_mfma_f32_16x16x32_bf16 v[54:57], v[166:169], v[186:189], v[54:57]
	v_mfma_f32_16x16x32_bf16 v[50:53], v[174:177], v[186:189], v[50:53]
	v_mfma_f32_16x16x32_bf16 v[38:41], v[166:169], v[216:219], v[38:41]
	v_mfma_f32_16x16x32_bf16 v[34:37], v[174:177], v[216:219], v[34:37]
	v_mfma_f32_16x16x32_bf16 v[22:25], v[166:169], v[224:227], v[22:25]
	v_mfma_f32_16x16x32_bf16 v[18:21], v[174:177], v[224:227], v[18:21]
	v_mfma_f32_16x16x32_bf16 v[6:9], v[166:169], v[236:239], v[6:9]
	v_mfma_f32_16x16x32_bf16 v[2:5], v[174:177], v[236:239], v[2:5]
	s_barrier
	s_add_u32 s8, s8, 0x100
	s_addc_u32 s9, s9, 0
	s_add_u32 s34, s34, 0x100
	s_addc_u32 s35, s35, 0
	s_cmp_ge_u32 s92, s12
	s_mov_b32 s26, s92
	s_cbranch_scc0 .LBB0_215
	s_setprio 0
	v_readlane_b32 s8, v250, 24
	v_readlane_b32 s9, v250, 25
	s_and_b64 vcc, exec, s[8:9]
	s_cbranch_vccz .LBB0_219
	s_barrier
	s_cmp_lt_i32 s96, 4
	s_mov_b64 s[8:9], -1
	s_cbranch_scc0 .LBB0_220

; template <bool COOP>
; __global__ void __launch_bounds__(512, 2) fwd_kernel(Params p) {
;     ...
;     }
; }
.LBB0_641:
	s_nop 0
	s_nop 0
	s_nop 0
	s_nop 0
	s_nop 0
	s_nop 0
	s_nop 0
	s_nop 0
	s_nop 0
	s_nop 0
	s_nop 0
	s_nop 0
	s_nop 0
	s_nop 0
	s_nop 0
	s_nop 0
	s_nop 0
	s_nop 0
	s_nop 0
	s_nop 0
	s_nop 0
	s_nop 0
	s_nop 0
	s_nop 0
	s_nop 0
	s_nop 0
	s_nop 0
	s_nop 0
	s_nop 0
	s_nop 0
	s_nop 0
	s_nop 0
	s_nop 0
	s_nop 0
	s_nop 0
	s_nop 0
	s_nop 0
	s_nop 0
	s_nop 0
	s_nop 0
	s_nop 0
	s_nop 0
	s_nop 0
	s_nop 0
	s_nop 0
	s_nop 0
	s_nop 0
	s_nop 0
	s_nop 0
	s_nop 0
	s_nop 0
	s_nop 0
	s_nop 0
	s_nop 0
	s_nop 0
	s_nop 0
	s_nop 0
	s_nop 0
	s_nop 0
	s_nop 0
	s_nop 0
	s_nop 0
	s_nop 0
	s_nop 0
	s_nop 0
	s_nop 0
	s_nop 0
	s_nop 0
	s_nop 0
	s_nop 0
	s_nop 0
	s_nop 0
	s_nop 0
	s_nop 0
	s_nop 0
	s_nop 0
	s_nop 0
	s_nop 0
	s_nop 0
	s_nop 0
	s_nop 0
	s_nop 0
	s_nop 0
	s_nop 0
	s_nop 0
	s_nop 0
	s_nop 0
	s_nop 0
	s_nop 0
	s_nop 0
	s_nop 0
	s_nop 0
	s_nop 0
	s_nop 0
	s_nop 0
	s_nop 0
	s_nop 0
	s_nop 0
	s_nop 0
	s_nop 0
	s_nop 0
	s_nop 0
	s_nop 0
	s_nop 0
	s_nop 0
	s_nop 0
	s_nop 0
	s_nop 0
	s_nop 0
	s_nop 0
	s_nop 0
	s_nop 0
	s_nop 0
	s_nop 0
	s_nop 0
	s_nop 0
	s_nop 0
	s_nop 0
	s_nop 0
	s_nop 0
	s_nop 0
	s_nop 0
	s_nop 0
	s_nop 0
	s_nop 0
	s_nop 0
	s_nop 0
	s_nop 0
	s_nop 0
	s_nop 0
	s_nop 0
	s_nop 0
	s_nop 0
	s_nop 0
	s_nop 0
	s_nop 0
	s_nop 0
	s_nop 0
	s_nop 0
	s_nop 0
	s_nop 0
	s_nop 0
	s_nop 0
	s_nop 0
	s_nop 0
	s_nop 0
	s_nop 0
	s_nop 0
	s_nop 0
	s_nop 0
	s_nop 0
	s_nop 0
	s_nop 0
	s_nop 0
	s_nop 0
	s_nop 0
	s_nop 0
	s_nop 0
	s_nop 0
	s_nop 0
	s_nop 0
	s_nop 0
	s_nop 0
	s_nop 0
	s_nop 0
	s_nop 0
	s_nop 0
	s_nop 0
	s_nop 0
	s_nop 0
	s_nop 0
	s_nop 0
	s_nop 0
	s_nop 0
	s_nop 0
	s_nop 0
	s_nop 0
	s_nop 0
	s_nop 0
	s_nop 0
	s_nop 0
	s_nop 0
	s_nop 0
	s_nop 0
	s_nop 0
	s_nop 0
	s_nop 0
	s_nop 0
	s_nop 0
	s_nop 0
	s_nop 0
	s_nop 0
	s_endpgm
